# attention epilogue row stores paired into dwordx4 with permlane32_swap
# baseline (speedup 1.0000x reference)
; __device__ __forceinline__ float half_swap_sum(float v) { auto rr = __builtin_amdgcn_permlane32_swap(__float_as_uint(v), __float_as_uint(v), false, false); return __uint_as_float(rr[0]) + __uint_as_float(rr[1]); }
; __device__ __forceinline__ void attn_item(LAS unsigned char* lds, const bf16_t* Q, const bf16_t* Kb, const bf16_t* VT, bf16_t* aout, const float* subg, float lam, float omli, float kbound, int head, int qb) {
;     ...
;     if (comp == 0) {
;         float ss = 0.f;
; #pragma unroll
;         for (int e = 0; e < 4; ++e)
; #pragma unroll
;             for (int i = 0; i < 16; ++i) { const float o = O[e][i] * inv - lam * X[(qt * 128 + 32 * e + (i & 3) + 8 * (i >> 2) + 4 * hh) * 32 + r]; O[e][i] = o; ss += o * o; }
;         ss = half_swap_sum(ss);
;         const float rn = __builtin_amdgcn_rsqf(ss * (1.f / 128.f) + EPS) * omli;
;         bf16_t* ap = aout + (size_t)q * 1024 + head * 128 + 4 * hh;
; #pragma unroll
;         for (int e = 0; e < 4; ++e)
; #pragma unroll
;             for (int g4 = 0; g4 < 4; ++g4) { const int e0 = 32 * e + 8 * g4; const f32x4 sg = *(const f32x4*)(subg + e0 + 4 * hh);
.LBB0_328:
	s_andn2_b64 vcc, exec, s[4:5]
	s_waitcnt lgkmcnt(0)
	s_barrier
	s_cbranch_vccnz .LBB0_330
	s_lshl_b32 s0, s0, 14
	v_add3_u32 v64, v65, v64, s0
	ds_read2_b32 v[90:91], v64 offset1:32
	ds_read2_b32 v[84:85], v64 offset0:64 offset1:96
	v_add_u32_e32 v65, 0x400, v64
	ds_read2_b32 v[94:95], v65 offset1:32
	ds_read2_b32 v[92:93], v65 offset0:64 offset1:96
	v_add_u32_e32 v65, 0x800, v64
	ds_read2_b32 v[102:103], v65 offset1:32
	ds_read2_b32 v[122:123], v65 offset0:64 offset1:96
	s_waitcnt lgkmcnt(4)
	v_pk_mul_f32 v[84:85], v[200:201], v[84:85]
	v_add_u32_e32 v65, 0xc00, v64
	v_pk_fma_f32 v[84:85], v[50:51], v[70:71], v[84:85] op_sel_hi:[1,0,1] neg_lo:[0,0,1] neg_hi:[0,0,1]
	v_pk_mul_f32 v[50:51], v[200:201], v[90:91]
	ds_read2_b32 v[124:125], v65 offset1:32
	ds_read2_b32 v[126:127], v65 offset0:64 offset1:96
	v_pk_fma_f32 v[90:91], v[48:49], v[70:71], v[50:51] op_sel_hi:[1,0,1] neg_lo:[0,0,1] neg_hi:[0,0,1]
	v_add_u32_e32 v65, 0x1000, v64
	v_mul_f32_e32 v48, v91, v91
	v_pk_fma_f32 v[48:49], v[90:91], v[90:91], v[48:49] op_sel_hi:[1,1,0]
	ds_read2_b32 v[128:129], v65 offset1:32
	s_waitcnt vmcnt(1)
	ds_read2_b32 v[130:131], v65 offset0:64 offset1:96
	v_add_u32_e32 v65, 0x1400, v64
	v_pk_fma_f32 v[48:49], v[84:85], v[84:85], v[48:49]
	v_mul_f32_e32 v50, v85, v85
	ds_read2_b32 v[132:133], v65 offset1:32
	s_waitcnt vmcnt(0)
	ds_read2_b32 v[134:135], v65 offset0:64 offset1:96
	v_add_u32_e32 v65, 0x1800, v64
	v_pk_add_f32 v[48:49], v[48:49], v[50:51] op_sel_hi:[1,0]
	s_waitcnt lgkmcnt(8)
	v_pk_mul_f32 v[50:51], v[200:201], v[92:93]
	ds_read2_b32 v[120:121], v65 offset1:32
	ds_read2_b32 v[136:137], v65 offset0:64 offset1:96
	v_add_u32_e32 v65, 0x1c00, v64
	v_pk_fma_f32 v[92:93], v[54:55], v[70:71], v[50:51] op_sel_hi:[1,0,1] neg_lo:[0,0,1] neg_hi:[0,0,1]
	v_pk_mul_f32 v[50:51], v[200:201], v[94:95]
	ds_read2_b32 v[116:117], v65 offset1:32
	ds_read2_b32 v[118:119], v65 offset0:64 offset1:96
	v_add_u32_e32 v65, 0x2000, v64
	v_pk_fma_f32 v[100:101], v[52:53], v[70:71], v[50:51] op_sel_hi:[1,0,1] neg_lo:[0,0,1] neg_hi:[0,0,1]
	ds_read2_b32 v[110:111], v65 offset1:32
	ds_read2_b32 v[114:115], v65 offset0:64 offset1:96
	v_add_u32_e32 v65, 0x2400, v64
	v_pk_fma_f32 v[48:49], v[100:101], v[100:101], v[48:49]
	v_mul_f32_e32 v50, v101, v101
	ds_read2_b32 v[106:107], v65 offset1:32
	ds_read2_b32 v[108:109], v65 offset0:64 offset1:96
	v_add_u32_e32 v65, 0x2800, v64
	v_pk_add_f32 v[48:49], v[48:49], v[50:51] op_sel_hi:[1,0]
	ds_read2_b32 v[98:99], v65 offset1:32
	ds_read2_b32 v[104:105], v65 offset0:64 offset1:96
	v_add_u32_e32 v65, 0x2c00, v64
	v_pk_fma_f32 v[48:49], v[92:93], v[92:93], v[48:49]
	v_mul_f32_e32 v50, v93, v93
	ds_read2_b32 v[88:89], v65 offset1:32
	ds_read2_b32 v[96:97], v65 offset0:64 offset1:96
	v_add_u32_e32 v65, 0x3000, v64
	v_pk_add_f32 v[48:49], v[48:49], v[50:51] op_sel_hi:[1,0]
	s_waitcnt lgkmcnt(14)
	v_pk_mul_f32 v[50:51], v[200:201], v[122:123]
	ds_read2_b32 v[82:83], v65 offset1:32
	ds_read2_b32 v[86:87], v65 offset0:64 offset1:96
	v_add_u32_e32 v65, 0x3400, v64
	v_pk_fma_f32 v[94:95], v[58:59], v[70:71], v[50:51] op_sel_hi:[1,0,1] neg_lo:[0,0,1] neg_hi:[0,0,1]
	v_pk_mul_f32 v[50:51], v[200:201], v[102:103]
	ds_read2_b32 v[78:79], v65 offset1:32
	ds_read2_b32 v[80:81], v65 offset0:64 offset1:96
	v_add_u32_e32 v65, 0x3800, v64
	v_add_u32_e32 v64, 0x3c00, v64
	v_pk_fma_f32 v[102:103], v[56:57], v[70:71], v[50:51] op_sel_hi:[1,0,1] neg_lo:[0,0,1] neg_hi:[0,0,1]
	ds_read2_b32 v[72:73], v65 offset1:32
	ds_read2_b32 v[76:77], v65 offset0:64 offset1:96
	ds_read2_b32 v[74:75], v64 offset1:32
	ds_read2_b32 v[64:65], v64 offset0:64 offset1:96
	v_pk_fma_f32 v[48:49], v[102:103], v[102:103], v[48:49]
	v_mul_f32_e32 v50, v103, v103
	v_pk_add_f32 v[48:49], v[48:49], v[50:51] op_sel_hi:[1,0]
	v_mul_f32_e32 v50, v95, v95
	v_pk_fma_f32 v[48:49], v[94:95], v[94:95], v[48:49]
	s_waitcnt lgkmcnt(0)
	v_pk_mul_f32 v[64:65], v[200:201], v[64:65]
	v_pk_add_f32 v[48:49], v[48:49], v[50:51] op_sel_hi:[1,0]
	v_pk_mul_f32 v[50:51], v[200:201], v[126:127]
	v_pk_fma_f32 v[68:69], v[14:15], v[70:71], v[64:65] op_sel_hi:[1,0,1] neg_lo:[0,0,1] neg_hi:[0,0,1]
	v_pk_fma_f32 v[58:59], v[62:63], v[70:71], v[50:51] op_sel_hi:[1,0,1] neg_lo:[0,0,1] neg_hi:[0,0,1]
	v_pk_mul_f32 v[50:51], v[200:201], v[124:125]
	v_lshlrev_b64 v[14:15], 11, v[202:203]
	v_pk_fma_f32 v[62:63], v[60:61], v[70:71], v[50:51] op_sel_hi:[1,0,1] neg_lo:[0,0,1] neg_hi:[0,0,1]
	v_lshl_add_u64 v[14:15], s[48:49], 0, v[14:15]
	v_pk_fma_f32 v[48:49], v[62:63], v[62:63], v[48:49]
	v_mul_f32_e32 v50, v63, v63
	s_lshl_b32 s58, s18, 8
	v_pk_add_f32 v[48:49], v[48:49], v[50:51] op_sel_hi:[1,0]
	v_lshl_add_u64 v[14:15], v[14:15], 0, s[58:59]
	v_lshlrev_b32_e32 v64, 3, v226
	v_mov_b32_e32 v65, v113
	v_pk_fma_f32 v[48:49], v[58:59], v[58:59], v[48:49]
	v_mul_f32_e32 v50, v59, v59
	v_lshl_add_u64 v[14:15], v[14:15], 0, v[64:65]
	global_load_dwordx4 v[64:67], v112, s[2:3]
	global_load_dwordx4 v[148:151], v112, s[2:3] offset:32
	global_load_dwordx4 v[152:155], v112, s[2:3] offset:64
	global_load_dwordx4 v[156:159], v112, s[2:3] offset:96
	global_load_dwordx4 v[160:163], v112, s[2:3] offset:128
	global_load_dwordx4 v[164:167], v112, s[2:3] offset:160
	global_load_dwordx4 v[168:171], v112, s[2:3] offset:192
	global_load_dwordx4 v[176:179], v112, s[2:3] offset:224
	global_load_dwordx4 v[184:187], v112, s[2:3] offset:256
	global_load_dwordx4 v[204:207], v112, s[2:3] offset:288
	global_load_dwordx4 v[208:211], v112, s[2:3] offset:320
	global_load_dwordx4 v[232:235], v112, s[2:3] offset:352
	global_load_dwordx4 v[236:239], v112, s[2:3] offset:384
	global_load_dwordx4 v[240:243], v112, s[2:3] offset:416
; __device__ __forceinline__ void attn_item(LAS unsigned char* lds, const bf16_t* Q, const bf16_t* Kb, const bf16_t* VT, bf16_t* aout, const float* subg, float lam, float omli, float kbound, int head, int qb) {
;     ...
;             for (int i = 0; i < 16; ++i) { const float o = O[e][i] * inv - lam * X[(qt * 128 + 32 * e + (i & 3) + 8 * (i >> 2) + 4 * hh) * 32 + r]; O[e][i] = o; ss += o * o; }
	global_load_dwordx4 v[244:247], v112, s[2:3] offset:448
	global_load_dwordx4 v[248:251], v112, s[2:3] offset:480
	v_pk_add_f32 v[48:49], v[48:49], v[50:51] op_sel_hi:[1,0]
	v_pk_mul_f32 v[50:51], v[200:201], v[130:131]
	s_nop 0
	v_pk_fma_f32 v[54:55], v[34:35], v[70:71], v[50:51] op_sel_hi:[1,0,1] neg_lo:[0,0,1] neg_hi:[0,0,1]
	v_pk_mul_f32 v[34:35], v[200:201], v[128:129]
	s_nop 0
	v_pk_fma_f32 v[60:61], v[32:33], v[70:71], v[34:35] op_sel_hi:[1,0,1] neg_lo:[0,0,1] neg_hi:[0,0,1]
	s_nop 0
	v_pk_fma_f32 v[32:33], v[60:61], v[60:61], v[48:49]
	v_mul_f32_e32 v34, v61, v61
	v_pk_add_f32 v[32:33], v[32:33], v[34:35] op_sel_hi:[1,0]
	v_mul_f32_e32 v34, v55, v55
	v_pk_fma_f32 v[32:33], v[54:55], v[54:55], v[32:33]
	s_nop 0
	v_pk_add_f32 v[32:33], v[32:33], v[34:35] op_sel_hi:[1,0]
	v_pk_mul_f32 v[34:35], v[200:201], v[134:135]
	s_nop 0
	v_pk_fma_f32 v[50:51], v[38:39], v[70:71], v[34:35] op_sel_hi:[1,0,1] neg_lo:[0,0,1] neg_hi:[0,0,1]
	v_pk_mul_f32 v[34:35], v[200:201], v[132:133]
	s_nop 0
	v_pk_fma_f32 v[56:57], v[36:37], v[70:71], v[34:35] op_sel_hi:[1,0,1] neg_lo:[0,0,1] neg_hi:[0,0,1]
	s_nop 0
	v_pk_fma_f32 v[32:33], v[56:57], v[56:57], v[32:33]
	v_mul_f32_e32 v34, v57, v57
	v_pk_add_f32 v[32:33], v[32:33], v[34:35] op_sel_hi:[1,0]
	v_mul_f32_e32 v34, v51, v51
	v_pk_fma_f32 v[32:33], v[50:51], v[50:51], v[32:33]
	s_nop 0
	v_pk_add_f32 v[32:33], v[32:33], v[34:35] op_sel_hi:[1,0]
	v_pk_mul_f32 v[34:35], v[200:201], v[136:137]
	s_nop 0
	v_pk_fma_f32 v[48:49], v[42:43], v[70:71], v[34:35] op_sel_hi:[1,0,1] neg_lo:[0,0,1] neg_hi:[0,0,1]
	v_pk_mul_f32 v[34:35], v[200:201], v[120:121]
	s_nop 0
	v_pk_fma_f32 v[52:53], v[40:41], v[70:71], v[34:35] op_sel_hi:[1,0,1] neg_lo:[0,0,1] neg_hi:[0,0,1]
	s_nop 0
	v_pk_fma_f32 v[32:33], v[52:53], v[52:53], v[32:33]
	v_mul_f32_e32 v34, v53, v53
	v_pk_add_f32 v[32:33], v[32:33], v[34:35] op_sel_hi:[1,0]
	v_mul_f32_e32 v34, v49, v49
	v_pk_fma_f32 v[32:33], v[48:49], v[48:49], v[32:33]
	s_nop 0
	v_pk_add_f32 v[32:33], v[32:33], v[34:35] op_sel_hi:[1,0]
	v_pk_mul_f32 v[34:35], v[200:201], v[118:119]
	s_nop 0
	v_pk_fma_f32 v[40:41], v[46:47], v[70:71], v[34:35] op_sel_hi:[1,0,1] neg_lo:[0,0,1] neg_hi:[0,0,1]
	v_pk_mul_f32 v[34:35], v[200:201], v[116:117]
	s_nop 0
	v_pk_fma_f32 v[44:45], v[44:45], v[70:71], v[34:35] op_sel_hi:[1,0,1] neg_lo:[0,0,1] neg_hi:[0,0,1]
	s_nop 0
	v_pk_fma_f32 v[32:33], v[44:45], v[44:45], v[32:33]
	v_mul_f32_e32 v34, v45, v45
	v_pk_add_f32 v[32:33], v[32:33], v[34:35] op_sel_hi:[1,0]
	v_mul_f32_e32 v34, v41, v41
	v_pk_fma_f32 v[32:33], v[40:41], v[40:41], v[32:33]
	s_nop 0
	v_pk_add_f32 v[32:33], v[32:33], v[34:35] op_sel_hi:[1,0]
	v_pk_mul_f32 v[34:35], v[200:201], v[114:115]
	s_nop 0
	v_pk_fma_f32 v[36:37], v[18:19], v[70:71], v[34:35] op_sel_hi:[1,0,1] neg_lo:[0,0,1] neg_hi:[0,0,1]
	v_pk_mul_f32 v[18:19], v[200:201], v[110:111]
	s_nop 0
	v_pk_fma_f32 v[42:43], v[16:17], v[70:71], v[18:19] op_sel_hi:[1,0,1] neg_lo:[0,0,1] neg_hi:[0,0,1]
	s_nop 0
	v_pk_fma_f32 v[16:17], v[42:43], v[42:43], v[32:33]
	v_mul_f32_e32 v18, v43, v43
	v_pk_add_f32 v[16:17], v[16:17], v[18:19] op_sel_hi:[1,0]
	v_mul_f32_e32 v18, v37, v37
	v_pk_fma_f32 v[16:17], v[36:37], v[36:37], v[16:17]
	s_nop 0
	v_pk_add_f32 v[16:17], v[16:17], v[18:19] op_sel_hi:[1,0]
	v_pk_mul_f32 v[18:19], v[200:201], v[108:109]
	s_nop 0
	v_pk_fma_f32 v[32:33], v[22:23], v[70:71], v[18:19] op_sel_hi:[1,0,1] neg_lo:[0,0,1] neg_hi:[0,0,1]
	v_pk_mul_f32 v[18:19], v[200:201], v[106:107]
	s_nop 0
	v_pk_fma_f32 v[38:39], v[20:21], v[70:71], v[18:19] op_sel_hi:[1,0,1] neg_lo:[0,0,1] neg_hi:[0,0,1]
	s_nop 0
	v_pk_fma_f32 v[16:17], v[38:39], v[38:39], v[16:17]
	v_mul_f32_e32 v18, v39, v39
	v_pk_add_f32 v[16:17], v[16:17], v[18:19] op_sel_hi:[1,0]
	v_mul_f32_e32 v18, v33, v33
	v_pk_fma_f32 v[16:17], v[32:33], v[32:33], v[16:17]
	s_nop 0
	v_pk_add_f32 v[16:17], v[16:17], v[18:19] op_sel_hi:[1,0]
	v_pk_mul_f32 v[18:19], v[200:201], v[104:105]
	s_nop 0
	v_pk_fma_f32 v[26:27], v[26:27], v[70:71], v[18:19] op_sel_hi:[1,0,1] neg_lo:[0,0,1] neg_hi:[0,0,1]
	v_pk_mul_f32 v[18:19], v[200:201], v[98:99]
	s_nop 0
	v_pk_fma_f32 v[34:35], v[24:25], v[70:71], v[18:19] op_sel_hi:[1,0,1] neg_lo:[0,0,1] neg_hi:[0,0,1]
	s_nop 0
	v_pk_fma_f32 v[16:17], v[34:35], v[34:35], v[16:17]
	v_mul_f32_e32 v18, v35, v35
	v_pk_add_f32 v[16:17], v[16:17], v[18:19] op_sel_hi:[1,0]
	v_mul_f32_e32 v18, v27, v27
	v_pk_fma_f32 v[16:17], v[26:27], v[26:27], v[16:17]
	s_nop 0
	v_pk_add_f32 v[16:17], v[16:17], v[18:19] op_sel_hi:[1,0]
	v_pk_mul_f32 v[18:19], v[200:201], v[96:97]
	s_nop 0
	v_pk_fma_f32 v[20:21], v[30:31], v[70:71], v[18:19] op_sel_hi:[1,0,1] neg_lo:[0,0,1] neg_hi:[0,0,1]
	v_pk_mul_f32 v[18:19], v[200:201], v[88:89]
	s_nop 0
	v_pk_fma_f32 v[24:25], v[28:29], v[70:71], v[18:19] op_sel_hi:[1,0,1] neg_lo:[0,0,1] neg_hi:[0,0,1]
	s_nop 0
	v_pk_fma_f32 v[16:17], v[24:25], v[24:25], v[16:17]
	v_mul_f32_e32 v18, v25, v25
	v_pk_add_f32 v[16:17], v[16:17], v[18:19] op_sel_hi:[1,0]
	v_mul_f32_e32 v18, v21, v21
	v_pk_fma_f32 v[16:17], v[20:21], v[20:21], v[16:17]
	s_nop 0
	v_pk_add_f32 v[18:19], v[16:17], v[18:19] op_sel_hi:[1,0]
	v_pk_mul_f32 v[16:17], v[200:201], v[86:87]
	s_nop 0
	v_pk_fma_f32 v[16:17], v[2:3], v[70:71], v[16:17] op_sel_hi:[1,0,1] neg_lo:[0,0,1] neg_hi:[0,0,1]
	v_pk_mul_f32 v[2:3], v[200:201], v[82:83]
	s_nop 0
	v_pk_fma_f32 v[22:23], v[0:1], v[70:71], v[2:3] op_sel_hi:[1,0,1] neg_lo:[0,0,1] neg_hi:[0,0,1]
	s_nop 0
	v_pk_fma_f32 v[0:1], v[22:23], v[22:23], v[18:19]
	v_mul_f32_e32 v2, v23, v23
	v_pk_add_f32 v[0:1], v[0:1], v[2:3] op_sel_hi:[1,0]
	v_mul_f32_e32 v2, v17, v17
	v_pk_fma_f32 v[0:1], v[16:17], v[16:17], v[0:1]
	s_nop 0
	v_pk_add_f32 v[0:1], v[0:1], v[2:3] op_sel_hi:[1,0]
; __device__ __forceinline__ float half_swap_sum(float v) { auto rr = __builtin_amdgcn_permlane32_swap(__float_as_uint(v), __float_as_uint(v), false, false); return __uint_as_float(rr[0]) + __uint_as_float(rr[1]); }
; __device__ __forceinline__ void attn_item(LAS unsigned char* lds, const bf16_t* Q, const bf16_t* Kb, const bf16_t* VT, bf16_t* aout, const float* subg, float lam, float omli, float kbound, int head, int qb) {
;     ...
;             for (int i = 0; i < 16; ++i) { const float o = O[e][i] * inv - lam * X[(qt * 128 + 32 * e + (i & 3) + 8 * (i >> 2) + 4 * hh) * 32 + r]; O[e][i] = o; ss += o * o; }
;         ss = half_swap_sum(ss);
;         const float rn = __builtin_amdgcn_rsqf(ss * (1.f / 128.f) + EPS) * omli;
	v_pk_mul_f32 v[2:3], v[200:201], v[80:81]
	s_nop 0
	v_pk_fma_f32 v[6:7], v[6:7], v[70:71], v[2:3] op_sel_hi:[1,0,1] neg_lo:[0,0,1] neg_hi:[0,0,1]
	v_pk_mul_f32 v[2:3], v[200:201], v[78:79]
	s_nop 0
	v_pk_fma_f32 v[18:19], v[4:5], v[70:71], v[2:3] op_sel_hi:[1,0,1] neg_lo:[0,0,1] neg_hi:[0,0,1]
	v_pk_mul_f32 v[4:5], v[200:201], v[72:73]
	v_pk_fma_f32 v[0:1], v[18:19], v[18:19], v[0:1]
	v_mul_f32_e32 v2, v19, v19
	v_pk_add_f32 v[0:1], v[0:1], v[2:3] op_sel_hi:[1,0]
	v_mul_f32_e32 v2, v7, v7
	v_pk_fma_f32 v[0:1], v[6:7], v[6:7], v[0:1]
	v_pk_fma_f32 v[4:5], v[8:9], v[70:71], v[4:5] op_sel_hi:[1,0,1] neg_lo:[0,0,1] neg_hi:[0,0,1]
	v_pk_add_f32 v[2:3], v[0:1], v[2:3] op_sel_hi:[1,0]
	v_pk_mul_f32 v[0:1], v[200:201], v[76:77]
	v_pk_fma_f32 v[2:3], v[4:5], v[4:5], v[2:3]
	v_mul_f32_e32 v8, v5, v5
	v_pk_fma_f32 v[0:1], v[10:11], v[70:71], v[0:1] op_sel_hi:[1,0,1] neg_lo:[0,0,1] neg_hi:[0,0,1]
	v_pk_add_f32 v[2:3], v[2:3], v[8:9] op_sel_hi:[1,0]
	v_mul_f32_e32 v8, v1, v1
	v_pk_fma_f32 v[2:3], v[0:1], v[0:1], v[2:3]
	s_nop 0
	v_pk_add_f32 v[8:9], v[2:3], v[8:9] op_sel_hi:[1,0]
	v_pk_mul_f32 v[2:3], v[200:201], v[74:75]
	s_nop 0
	v_pk_fma_f32 v[2:3], v[12:13], v[70:71], v[2:3] op_sel_hi:[1,0,1] neg_lo:[0,0,1] neg_hi:[0,0,1]
	s_nop 0
	v_pk_fma_f32 v[8:9], v[2:3], v[2:3], v[8:9]
	v_mul_f32_e32 v10, v3, v3
	v_pk_add_f32 v[8:9], v[8:9], v[10:11] op_sel_hi:[1,0]
	v_mul_f32_e32 v10, v69, v69
	v_pk_fma_f32 v[8:9], v[68:69], v[68:69], v[8:9]
	s_nop 0
	v_pk_add_f32 v[8:9], v[8:9], v[10:11] op_sel_hi:[1,0]
	s_nop 0
	v_mov_b32_e32 v9, v8
	s_nop 1
	v_permlane32_swap_b32_e32 v8, v9
	v_add_f32_e32 v8, v8, v9
	v_fmamk_f32 v8, v8, 0x3c000000, v217
	v_rsq_f32_e32 v8, v8
	s_nop 0
	v_mul_f32_e32 v8, v224, v8
	v_pk_mul_f32 v[10:11], v[90:91], v[8:9] op_sel_hi:[1,0]
	v_pk_mul_f32 v[12:13], v[84:85], v[8:9] op_sel_hi:[1,0]
	s_waitcnt vmcnt(0)
; __device__ __forceinline__ unsigned pk2(float lo, float hi) { f32x2 v = {lo, hi}; bf16x2_t b = __builtin_convertvector(v, bf16x2_t); return __builtin_bit_cast(unsigned, b); }
; __device__ __forceinline__ void attn_item(LAS unsigned char* lds, const bf16_t* Q, const bf16_t* Kb, const bf16_t* VT, bf16_t* aout, const float* subg, float lam, float omli, float kbound, int head, int qb) {
;     ...
;         bf16_t* ap = aout + (size_t)q * 1024 + head * 128 + 4 * hh;
; #pragma unroll
;         for (int e = 0; e < 4; ++e)
; #pragma unroll
;             for (int g4 = 0; g4 < 4; ++g4) { const int e0 = 32 * e + 8 * g4; const f32x4 sg = *(const f32x4*)(subg + e0 + 4 * hh);
;                 u32x2 w; w.x = pk2(O[e][4 * g4 + 0] * rn * sg[0], O[e][4 * g4 + 1] * rn * sg[1]); w.y = pk2(O[e][4 * g4 + 2] * rn * sg[2], O[e][4 * g4 + 3] * rn * sg[3]);
;                 *(u32x2*)(ap + e0) = w; }
	v_pk_mul_f32 v[10:11], v[64:65], v[10:11]
	v_pk_mul_f32 v[12:13], v[66:67], v[12:13]
	v_cvt_pk_bf16_f32 v140, v10, v11
	v_cvt_pk_bf16_f32 v141, v12, v13
	v_pk_mul_f32 v[28:29], v[100:101], v[8:9] op_sel_hi:[1,0]
	v_pk_mul_f32 v[26:27], v[26:27], v[8:9] op_sel_hi:[1,0]
	v_pk_mul_f32 v[24:25], v[24:25], v[8:9] op_sel_hi:[1,0]
	v_pk_mul_f32 v[20:21], v[20:21], v[8:9] op_sel_hi:[1,0]
	v_pk_mul_f32 v[16:17], v[16:17], v[8:9] op_sel_hi:[1,0]
	v_pk_mul_f32 v[6:7], v[6:7], v[8:9] op_sel_hi:[1,0]
	v_pk_mul_f32 v[4:5], v[4:5], v[8:9] op_sel_hi:[1,0]
	v_pk_mul_f32 v[0:1], v[0:1], v[8:9] op_sel_hi:[1,0]
	v_pk_mul_f32 v[10:11], v[148:149], v[28:29]
	v_pk_mul_f32 v[28:29], v[92:93], v[8:9] op_sel_hi:[1,0]
	v_cvt_pk_bf16_f32 v142, v10, v11
	v_pk_mul_f32 v[12:13], v[150:151], v[28:29]
	v_pk_mul_f32 v[28:29], v[102:103], v[8:9] op_sel_hi:[1,0]
	v_cvt_pk_bf16_f32 v143, v12, v13
	v_lshrrev_b32_e32 v136, 1, v112
	v_mov_b32_e32 v137, 0
	v_lshl_add_u64 v[136:137], v[14:15], 0, v[136:137]
	s_nop 1
	v_permlane32_swap_b32_e32 v140, v142
	v_permlane32_swap_b32_e32 v141, v143
	global_store_dwordx4 v[136:137], v[140:143], off
	v_pk_mul_f32 v[10:11], v[152:153], v[28:29]
	v_pk_mul_f32 v[28:29], v[94:95], v[8:9] op_sel_hi:[1,0]
	v_cvt_pk_bf16_f32 v144, v10, v11
	v_pk_mul_f32 v[12:13], v[154:155], v[28:29]
	v_pk_mul_f32 v[28:29], v[62:63], v[8:9] op_sel_hi:[1,0]
	v_cvt_pk_bf16_f32 v145, v12, v13
	v_pk_mul_f32 v[10:11], v[156:157], v[28:29]
	v_pk_mul_f32 v[28:29], v[58:59], v[8:9] op_sel_hi:[1,0]
	v_cvt_pk_bf16_f32 v146, v10, v11
	v_pk_mul_f32 v[12:13], v[158:159], v[28:29]
	v_pk_mul_f32 v[28:29], v[60:61], v[8:9] op_sel_hi:[1,0]
	v_cvt_pk_bf16_f32 v147, v12, v13
	s_nop 1
	v_permlane32_swap_b32_e32 v144, v146
	v_permlane32_swap_b32_e32 v145, v147
	global_store_dwordx4 v[136:137], v[144:147], off offset:32
	v_pk_mul_f32 v[10:11], v[28:29], v[160:161]
	v_pk_mul_f32 v[28:29], v[54:55], v[8:9] op_sel_hi:[1,0]
	v_cvt_pk_bf16_f32 v140, v10, v11
	v_pk_mul_f32 v[12:13], v[28:29], v[162:163]
	v_pk_mul_f32 v[28:29], v[56:57], v[8:9] op_sel_hi:[1,0]
	v_cvt_pk_bf16_f32 v141, v12, v13
	v_pk_mul_f32 v[10:11], v[28:29], v[164:165]
	v_pk_mul_f32 v[28:29], v[50:51], v[8:9] op_sel_hi:[1,0]
	v_cvt_pk_bf16_f32 v142, v10, v11
	v_pk_mul_f32 v[12:13], v[28:29], v[166:167]
	v_pk_mul_f32 v[28:29], v[52:53], v[8:9] op_sel_hi:[1,0]
	v_cvt_pk_bf16_f32 v143, v12, v13
	s_nop 1
	v_permlane32_swap_b32_e32 v140, v142
	v_permlane32_swap_b32_e32 v141, v143
	global_store_dwordx4 v[136:137], v[140:143], off offset:64
	v_pk_mul_f32 v[10:11], v[28:29], v[168:169]
	v_pk_mul_f32 v[28:29], v[48:49], v[8:9] op_sel_hi:[1,0]
	v_cvt_pk_bf16_f32 v144, v10, v11
	v_pk_mul_f32 v[12:13], v[28:29], v[170:171]
	v_pk_mul_f32 v[28:29], v[44:45], v[8:9] op_sel_hi:[1,0]
	v_cvt_pk_bf16_f32 v145, v12, v13
	v_pk_mul_f32 v[10:11], v[28:29], v[176:177]
	v_pk_mul_f32 v[28:29], v[40:41], v[8:9] op_sel_hi:[1,0]
	v_cvt_pk_bf16_f32 v146, v10, v11
	v_pk_mul_f32 v[12:13], v[28:29], v[178:179]
	v_pk_mul_f32 v[28:29], v[42:43], v[8:9] op_sel_hi:[1,0]
	v_cvt_pk_bf16_f32 v147, v12, v13
	s_nop 1
	v_permlane32_swap_b32_e32 v144, v146
	v_permlane32_swap_b32_e32 v145, v147
	global_store_dwordx4 v[136:137], v[144:147], off offset:96
	v_pk_mul_f32 v[10:11], v[28:29], v[184:185]
	v_pk_mul_f32 v[28:29], v[36:37], v[8:9] op_sel_hi:[1,0]
	v_cvt_pk_bf16_f32 v140, v10, v11
	v_pk_mul_f32 v[12:13], v[28:29], v[186:187]
	v_pk_mul_f32 v[28:29], v[38:39], v[8:9] op_sel_hi:[1,0]
	v_cvt_pk_bf16_f32 v141, v12, v13
	v_pk_mul_f32 v[10:11], v[28:29], v[204:205]
	v_pk_mul_f32 v[28:29], v[32:33], v[8:9] op_sel_hi:[1,0]
	v_cvt_pk_bf16_f32 v142, v10, v11
	v_pk_mul_f32 v[12:13], v[28:29], v[206:207]
	v_pk_mul_f32 v[28:29], v[34:35], v[8:9] op_sel_hi:[1,0]
	v_cvt_pk_bf16_f32 v143, v12, v13
	s_nop 1
	v_permlane32_swap_b32_e32 v140, v142
	v_permlane32_swap_b32_e32 v141, v143
	global_store_dwordx4 v[136:137], v[140:143], off offset:128
	v_pk_mul_f32 v[10:11], v[28:29], v[208:209]
	v_pk_mul_f32 v[12:13], v[26:27], v[210:211]
	v_cvt_pk_bf16_f32 v144, v10, v11
	v_cvt_pk_bf16_f32 v145, v12, v13
	v_pk_mul_f32 v[10:11], v[24:25], v[232:233]
	v_pk_mul_f32 v[12:13], v[20:21], v[234:235]
	v_cvt_pk_bf16_f32 v146, v10, v11
	v_cvt_pk_bf16_f32 v147, v12, v13
	s_nop 1
	v_permlane32_swap_b32_e32 v144, v146
	v_permlane32_swap_b32_e32 v145, v147
	global_store_dwordx4 v[136:137], v[144:147], off offset:160
	v_pk_mul_f32 v[20:21], v[22:23], v[8:9] op_sel_hi:[1,0]
	v_pk_mul_f32 v[12:13], v[16:17], v[238:239]
	v_pk_mul_f32 v[10:11], v[20:21], v[236:237]
	v_pk_mul_f32 v[16:17], v[18:19], v[8:9] op_sel_hi:[1,0]
	v_cvt_pk_bf16_f32 v140, v10, v11
	v_cvt_pk_bf16_f32 v141, v12, v13
	v_pk_mul_f32 v[10:11], v[16:17], v[240:241]
	v_pk_mul_f32 v[6:7], v[6:7], v[242:243]
	v_cvt_pk_bf16_f32 v142, v10, v11
	v_cvt_pk_bf16_f32 v143, v6, v7
	s_nop 1
	v_permlane32_swap_b32_e32 v140, v142
	v_permlane32_swap_b32_e32 v141, v143
	global_store_dwordx4 v[136:137], v[140:143], off offset:192
	v_pk_mul_f32 v[4:5], v[4:5], v[244:245]
	v_pk_mul_f32 v[0:1], v[0:1], v[246:247]
	v_cvt_pk_bf16_f32 v144, v4, v5
	v_cvt_pk_bf16_f32 v145, v0, v1
	v_pk_mul_f32 v[0:1], v[2:3], v[8:9] op_sel_hi:[1,0]
	v_pk_mul_f32 v[2:3], v[68:69], v[8:9] op_sel_hi:[1,0]
	v_pk_mul_f32 v[0:1], v[0:1], v[248:249]
	v_pk_mul_f32 v[2:3], v[2:3], v[250:251]
	v_cvt_pk_bf16_f32 v146, v0, v1
	v_cvt_pk_bf16_f32 v147, v2, v3
	s_nop 1
	v_permlane32_swap_b32_e32 v144, v146
	v_permlane32_swap_b32_e32 v145, v147
	global_store_dwordx4 v[136:137], v[144:147], off offset:224

; __device__ __forceinline__ float half_swap_sum(float v) { auto rr = __builtin_amdgcn_permlane32_swap(__float_as_uint(v), __float_as_uint(v), false, false); return __uint_as_float(rr[0]) + __uint_as_float(rr[1]); }
; __device__ __forceinline__ void attn_item(LAS unsigned char* lds, const bf16_t* Q, const bf16_t* Kb, const bf16_t* VT, bf16_t* aout, const float* subg, float lam, float omli, float kbound, int head, int qb) {
;     ...
;     if (comp == 0) {
;         float ss = 0.f;
; #pragma unroll
;         for (int e = 0; e < 4; ++e)
; #pragma unroll
;             for (int i = 0; i < 16; ++i) { const float o = O[e][i] * inv - lam * X[(qt * 128 + 32 * e + (i & 3) + 8 * (i >> 2) + 4 * hh) * 32 + r]; O[e][i] = o; ss += o * o; }
;         ss = half_swap_sum(ss);
;         const float rn = __builtin_amdgcn_rsqf(ss * (1.f / 128.f) + EPS) * omli;
;         bf16_t* ap = aout + (size_t)q * 1024 + head * 128 + 4 * hh;
; #pragma unroll
;         for (int e = 0; e < 4; ++e)
; #pragma unroll
;             for (int g4 = 0; g4 < 4; ++g4) { const int e0 = 32 * e + 8 * g4; const f32x4 sg = *(const f32x4*)(subg + e0 + 4 * hh);
.LBB0_366:
	s_andn2_b64 vcc, exec, s[4:5]
	s_waitcnt lgkmcnt(0)
	s_barrier
	s_cbranch_vccnz .LBB0_291
	s_lshl_b32 s0, s0, 14
	v_add3_u32 v64, v65, v64, s0
	ds_read2_b32 v[90:91], v64 offset1:32
	ds_read2_b32 v[84:85], v64 offset0:64 offset1:96
	v_add_u32_e32 v65, 0x400, v64
	ds_read2_b32 v[94:95], v65 offset1:32
	ds_read2_b32 v[92:93], v65 offset0:64 offset1:96
	v_add_u32_e32 v65, 0x800, v64
	ds_read2_b32 v[102:103], v65 offset1:32
	ds_read2_b32 v[122:123], v65 offset0:64 offset1:96
	s_waitcnt lgkmcnt(4)
	v_pk_mul_f32 v[84:85], v[200:201], v[84:85]
	v_add_u32_e32 v65, 0xc00, v64
	v_pk_fma_f32 v[84:85], v[50:51], v[70:71], v[84:85] op_sel_hi:[1,0,1] neg_lo:[0,0,1] neg_hi:[0,0,1]
	v_pk_mul_f32 v[50:51], v[200:201], v[90:91]
	ds_read2_b32 v[124:125], v65 offset1:32
	ds_read2_b32 v[126:127], v65 offset0:64 offset1:96
	v_pk_fma_f32 v[90:91], v[48:49], v[70:71], v[50:51] op_sel_hi:[1,0,1] neg_lo:[0,0,1] neg_hi:[0,0,1]
	v_add_u32_e32 v65, 0x1000, v64
	v_mul_f32_e32 v48, v91, v91
	v_pk_fma_f32 v[48:49], v[90:91], v[90:91], v[48:49] op_sel_hi:[1,1,0]
	ds_read2_b32 v[128:129], v65 offset1:32
	s_waitcnt vmcnt(1)
	ds_read2_b32 v[130:131], v65 offset0:64 offset1:96
	v_add_u32_e32 v65, 0x1400, v64
	v_pk_fma_f32 v[48:49], v[84:85], v[84:85], v[48:49]
	v_mul_f32_e32 v50, v85, v85
	ds_read2_b32 v[132:133], v65 offset1:32
	s_waitcnt vmcnt(0)
	ds_read2_b32 v[134:135], v65 offset0:64 offset1:96
	v_add_u32_e32 v65, 0x1800, v64
	v_pk_add_f32 v[48:49], v[48:49], v[50:51] op_sel_hi:[1,0]
	s_waitcnt lgkmcnt(8)
	v_pk_mul_f32 v[50:51], v[200:201], v[92:93]
	ds_read2_b32 v[120:121], v65 offset1:32
	ds_read2_b32 v[136:137], v65 offset0:64 offset1:96
	v_add_u32_e32 v65, 0x1c00, v64
	v_pk_fma_f32 v[92:93], v[54:55], v[70:71], v[50:51] op_sel_hi:[1,0,1] neg_lo:[0,0,1] neg_hi:[0,0,1]
	v_pk_mul_f32 v[50:51], v[200:201], v[94:95]
	ds_read2_b32 v[116:117], v65 offset1:32
	ds_read2_b32 v[118:119], v65 offset0:64 offset1:96
	v_add_u32_e32 v65, 0x2000, v64
	v_pk_fma_f32 v[100:101], v[52:53], v[70:71], v[50:51] op_sel_hi:[1,0,1] neg_lo:[0,0,1] neg_hi:[0,0,1]
	ds_read2_b32 v[110:111], v65 offset1:32
	ds_read2_b32 v[114:115], v65 offset0:64 offset1:96
	v_add_u32_e32 v65, 0x2400, v64
	v_pk_fma_f32 v[48:49], v[100:101], v[100:101], v[48:49]
	v_mul_f32_e32 v50, v101, v101
	ds_read2_b32 v[106:107], v65 offset1:32
	ds_read2_b32 v[108:109], v65 offset0:64 offset1:96
	v_add_u32_e32 v65, 0x2800, v64
	v_pk_add_f32 v[48:49], v[48:49], v[50:51] op_sel_hi:[1,0]
	ds_read2_b32 v[98:99], v65 offset1:32
	ds_read2_b32 v[104:105], v65 offset0:64 offset1:96
	v_add_u32_e32 v65, 0x2c00, v64
	v_pk_fma_f32 v[48:49], v[92:93], v[92:93], v[48:49]
	v_mul_f32_e32 v50, v93, v93
	ds_read2_b32 v[88:89], v65 offset1:32
	ds_read2_b32 v[96:97], v65 offset0:64 offset1:96
	v_add_u32_e32 v65, 0x3000, v64
	v_pk_add_f32 v[48:49], v[48:49], v[50:51] op_sel_hi:[1,0]
	s_waitcnt lgkmcnt(14)
	v_pk_mul_f32 v[50:51], v[200:201], v[122:123]
	ds_read2_b32 v[82:83], v65 offset1:32
	ds_read2_b32 v[86:87], v65 offset0:64 offset1:96
	v_add_u32_e32 v65, 0x3400, v64
	v_pk_fma_f32 v[94:95], v[58:59], v[70:71], v[50:51] op_sel_hi:[1,0,1] neg_lo:[0,0,1] neg_hi:[0,0,1]
	v_pk_mul_f32 v[50:51], v[200:201], v[102:103]
	ds_read2_b32 v[78:79], v65 offset1:32
	ds_read2_b32 v[80:81], v65 offset0:64 offset1:96
	v_add_u32_e32 v65, 0x3800, v64
	v_add_u32_e32 v64, 0x3c00, v64
	v_pk_fma_f32 v[102:103], v[56:57], v[70:71], v[50:51] op_sel_hi:[1,0,1] neg_lo:[0,0,1] neg_hi:[0,0,1]
	ds_read2_b32 v[72:73], v65 offset1:32
	ds_read2_b32 v[76:77], v65 offset0:64 offset1:96
	ds_read2_b32 v[74:75], v64 offset1:32
	ds_read2_b32 v[64:65], v64 offset0:64 offset1:96
	v_pk_fma_f32 v[48:49], v[102:103], v[102:103], v[48:49]
	v_mul_f32_e32 v50, v103, v103
	v_pk_add_f32 v[48:49], v[48:49], v[50:51] op_sel_hi:[1,0]
	v_mul_f32_e32 v50, v95, v95
	v_pk_fma_f32 v[48:49], v[94:95], v[94:95], v[48:49]
	s_waitcnt lgkmcnt(0)
	v_pk_mul_f32 v[64:65], v[200:201], v[64:65]
	v_pk_add_f32 v[48:49], v[48:49], v[50:51] op_sel_hi:[1,0]
	v_pk_mul_f32 v[50:51], v[200:201], v[126:127]
	v_pk_fma_f32 v[68:69], v[14:15], v[70:71], v[64:65] op_sel_hi:[1,0,1] neg_lo:[0,0,1] neg_hi:[0,0,1]
	v_pk_fma_f32 v[58:59], v[62:63], v[70:71], v[50:51] op_sel_hi:[1,0,1] neg_lo:[0,0,1] neg_hi:[0,0,1]
	v_pk_mul_f32 v[50:51], v[200:201], v[124:125]
	v_lshlrev_b64 v[14:15], 11, v[202:203]
	v_pk_fma_f32 v[62:63], v[60:61], v[70:71], v[50:51] op_sel_hi:[1,0,1] neg_lo:[0,0,1] neg_hi:[0,0,1]
	v_lshl_add_u64 v[14:15], s[48:49], 0, v[14:15]
	v_pk_fma_f32 v[48:49], v[62:63], v[62:63], v[48:49]
	v_mul_f32_e32 v50, v63, v63
	s_lshl_b32 s58, s18, 8
	v_pk_add_f32 v[48:49], v[48:49], v[50:51] op_sel_hi:[1,0]
	v_lshl_add_u64 v[14:15], v[14:15], 0, s[58:59]
	v_lshlrev_b32_e32 v64, 3, v226
	v_mov_b32_e32 v65, v113
	v_pk_fma_f32 v[48:49], v[58:59], v[58:59], v[48:49]
	v_mul_f32_e32 v50, v59, v59
	v_lshl_add_u64 v[14:15], v[14:15], 0, v[64:65]
	global_load_dwordx4 v[64:67], v112, s[2:3]
	global_load_dwordx4 v[148:151], v112, s[2:3] offset:32
	global_load_dwordx4 v[152:155], v112, s[2:3] offset:64
	global_load_dwordx4 v[156:159], v112, s[2:3] offset:96
	global_load_dwordx4 v[160:163], v112, s[2:3] offset:128
	global_load_dwordx4 v[164:167], v112, s[2:3] offset:160
	global_load_dwordx4 v[168:171], v112, s[2:3] offset:192
	global_load_dwordx4 v[176:179], v112, s[2:3] offset:224
	global_load_dwordx4 v[184:187], v112, s[2:3] offset:256
	global_load_dwordx4 v[204:207], v112, s[2:3] offset:288
	global_load_dwordx4 v[208:211], v112, s[2:3] offset:320
	global_load_dwordx4 v[232:235], v112, s[2:3] offset:352
	global_load_dwordx4 v[236:239], v112, s[2:3] offset:384
	global_load_dwordx4 v[240:243], v112, s[2:3] offset:416
; __device__ __forceinline__ void attn_item(LAS unsigned char* lds, const bf16_t* Q, const bf16_t* Kb, const bf16_t* VT, bf16_t* aout, const float* subg, float lam, float omli, float kbound, int head, int qb) {
;     ...
;             for (int i = 0; i < 16; ++i) { const float o = O[e][i] * inv - lam * X[(qt * 128 + 32 * e + (i & 3) + 8 * (i >> 2) + 4 * hh) * 32 + r]; O[e][i] = o; ss += o * o; }
	global_load_dwordx4 v[244:247], v112, s[2:3] offset:448
	global_load_dwordx4 v[248:251], v112, s[2:3] offset:480
	v_pk_add_f32 v[48:49], v[48:49], v[50:51] op_sel_hi:[1,0]
	v_pk_mul_f32 v[50:51], v[200:201], v[130:131]
	s_nop 0
	v_pk_fma_f32 v[54:55], v[34:35], v[70:71], v[50:51] op_sel_hi:[1,0,1] neg_lo:[0,0,1] neg_hi:[0,0,1]
	v_pk_mul_f32 v[34:35], v[200:201], v[128:129]
	s_nop 0
	v_pk_fma_f32 v[60:61], v[32:33], v[70:71], v[34:35] op_sel_hi:[1,0,1] neg_lo:[0,0,1] neg_hi:[0,0,1]
	s_nop 0
	v_pk_fma_f32 v[32:33], v[60:61], v[60:61], v[48:49]
	v_mul_f32_e32 v34, v61, v61
	v_pk_add_f32 v[32:33], v[32:33], v[34:35] op_sel_hi:[1,0]
	v_mul_f32_e32 v34, v55, v55
	v_pk_fma_f32 v[32:33], v[54:55], v[54:55], v[32:33]
	s_nop 0
	v_pk_add_f32 v[32:33], v[32:33], v[34:35] op_sel_hi:[1,0]
	v_pk_mul_f32 v[34:35], v[200:201], v[134:135]
	s_nop 0
	v_pk_fma_f32 v[50:51], v[38:39], v[70:71], v[34:35] op_sel_hi:[1,0,1] neg_lo:[0,0,1] neg_hi:[0,0,1]
	v_pk_mul_f32 v[34:35], v[200:201], v[132:133]
	s_nop 0
	v_pk_fma_f32 v[56:57], v[36:37], v[70:71], v[34:35] op_sel_hi:[1,0,1] neg_lo:[0,0,1] neg_hi:[0,0,1]
	s_nop 0
	v_pk_fma_f32 v[32:33], v[56:57], v[56:57], v[32:33]
	v_mul_f32_e32 v34, v57, v57
	v_pk_add_f32 v[32:33], v[32:33], v[34:35] op_sel_hi:[1,0]
	v_mul_f32_e32 v34, v51, v51
	v_pk_fma_f32 v[32:33], v[50:51], v[50:51], v[32:33]
	s_nop 0
	v_pk_add_f32 v[32:33], v[32:33], v[34:35] op_sel_hi:[1,0]
	v_pk_mul_f32 v[34:35], v[200:201], v[136:137]
	s_nop 0
	v_pk_fma_f32 v[48:49], v[42:43], v[70:71], v[34:35] op_sel_hi:[1,0,1] neg_lo:[0,0,1] neg_hi:[0,0,1]
	v_pk_mul_f32 v[34:35], v[200:201], v[120:121]
	s_nop 0
	v_pk_fma_f32 v[52:53], v[40:41], v[70:71], v[34:35] op_sel_hi:[1,0,1] neg_lo:[0,0,1] neg_hi:[0,0,1]
	s_nop 0
	v_pk_fma_f32 v[32:33], v[52:53], v[52:53], v[32:33]
	v_mul_f32_e32 v34, v53, v53
	v_pk_add_f32 v[32:33], v[32:33], v[34:35] op_sel_hi:[1,0]
	v_mul_f32_e32 v34, v49, v49
	v_pk_fma_f32 v[32:33], v[48:49], v[48:49], v[32:33]
	s_nop 0
	v_pk_add_f32 v[32:33], v[32:33], v[34:35] op_sel_hi:[1,0]
	v_pk_mul_f32 v[34:35], v[200:201], v[118:119]
	s_nop 0
	v_pk_fma_f32 v[40:41], v[46:47], v[70:71], v[34:35] op_sel_hi:[1,0,1] neg_lo:[0,0,1] neg_hi:[0,0,1]
	v_pk_mul_f32 v[34:35], v[200:201], v[116:117]
	s_nop 0
	v_pk_fma_f32 v[44:45], v[44:45], v[70:71], v[34:35] op_sel_hi:[1,0,1] neg_lo:[0,0,1] neg_hi:[0,0,1]
	s_nop 0
	v_pk_fma_f32 v[32:33], v[44:45], v[44:45], v[32:33]
	v_mul_f32_e32 v34, v45, v45
	v_pk_add_f32 v[32:33], v[32:33], v[34:35] op_sel_hi:[1,0]
	v_mul_f32_e32 v34, v41, v41
	v_pk_fma_f32 v[32:33], v[40:41], v[40:41], v[32:33]
	s_nop 0
	v_pk_add_f32 v[32:33], v[32:33], v[34:35] op_sel_hi:[1,0]
	v_pk_mul_f32 v[34:35], v[200:201], v[114:115]
	s_nop 0
	v_pk_fma_f32 v[36:37], v[18:19], v[70:71], v[34:35] op_sel_hi:[1,0,1] neg_lo:[0,0,1] neg_hi:[0,0,1]
	v_pk_mul_f32 v[18:19], v[200:201], v[110:111]
	s_nop 0
	v_pk_fma_f32 v[42:43], v[16:17], v[70:71], v[18:19] op_sel_hi:[1,0,1] neg_lo:[0,0,1] neg_hi:[0,0,1]
	s_nop 0
	v_pk_fma_f32 v[16:17], v[42:43], v[42:43], v[32:33]
	v_mul_f32_e32 v18, v43, v43
	v_pk_add_f32 v[16:17], v[16:17], v[18:19] op_sel_hi:[1,0]
	v_mul_f32_e32 v18, v37, v37
	v_pk_fma_f32 v[16:17], v[36:37], v[36:37], v[16:17]
	s_nop 0
	v_pk_add_f32 v[16:17], v[16:17], v[18:19] op_sel_hi:[1,0]
	v_pk_mul_f32 v[18:19], v[200:201], v[108:109]
	s_nop 0
	v_pk_fma_f32 v[32:33], v[22:23], v[70:71], v[18:19] op_sel_hi:[1,0,1] neg_lo:[0,0,1] neg_hi:[0,0,1]
	v_pk_mul_f32 v[18:19], v[200:201], v[106:107]
	s_nop 0
	v_pk_fma_f32 v[38:39], v[20:21], v[70:71], v[18:19] op_sel_hi:[1,0,1] neg_lo:[0,0,1] neg_hi:[0,0,1]
	s_nop 0
	v_pk_fma_f32 v[16:17], v[38:39], v[38:39], v[16:17]
	v_mul_f32_e32 v18, v39, v39
	v_pk_add_f32 v[16:17], v[16:17], v[18:19] op_sel_hi:[1,0]
	v_mul_f32_e32 v18, v33, v33
	v_pk_fma_f32 v[16:17], v[32:33], v[32:33], v[16:17]
	s_nop 0
	v_pk_add_f32 v[16:17], v[16:17], v[18:19] op_sel_hi:[1,0]
	v_pk_mul_f32 v[18:19], v[200:201], v[104:105]
	s_nop 0
	v_pk_fma_f32 v[26:27], v[26:27], v[70:71], v[18:19] op_sel_hi:[1,0,1] neg_lo:[0,0,1] neg_hi:[0,0,1]
	v_pk_mul_f32 v[18:19], v[200:201], v[98:99]
	s_nop 0
	v_pk_fma_f32 v[34:35], v[24:25], v[70:71], v[18:19] op_sel_hi:[1,0,1] neg_lo:[0,0,1] neg_hi:[0,0,1]
	s_nop 0
	v_pk_fma_f32 v[16:17], v[34:35], v[34:35], v[16:17]
	v_mul_f32_e32 v18, v35, v35
	v_pk_add_f32 v[16:17], v[16:17], v[18:19] op_sel_hi:[1,0]
	v_mul_f32_e32 v18, v27, v27
	v_pk_fma_f32 v[16:17], v[26:27], v[26:27], v[16:17]
	s_nop 0
	v_pk_add_f32 v[16:17], v[16:17], v[18:19] op_sel_hi:[1,0]
	v_pk_mul_f32 v[18:19], v[200:201], v[96:97]
	s_nop 0
	v_pk_fma_f32 v[20:21], v[30:31], v[70:71], v[18:19] op_sel_hi:[1,0,1] neg_lo:[0,0,1] neg_hi:[0,0,1]
	v_pk_mul_f32 v[18:19], v[200:201], v[88:89]
	s_nop 0
	v_pk_fma_f32 v[24:25], v[28:29], v[70:71], v[18:19] op_sel_hi:[1,0,1] neg_lo:[0,0,1] neg_hi:[0,0,1]
	s_nop 0
	v_pk_fma_f32 v[16:17], v[24:25], v[24:25], v[16:17]
	v_mul_f32_e32 v18, v25, v25
	v_pk_add_f32 v[16:17], v[16:17], v[18:19] op_sel_hi:[1,0]
	v_mul_f32_e32 v18, v21, v21
	v_pk_fma_f32 v[16:17], v[20:21], v[20:21], v[16:17]
	s_nop 0
	v_pk_add_f32 v[18:19], v[16:17], v[18:19] op_sel_hi:[1,0]
	v_pk_mul_f32 v[16:17], v[200:201], v[86:87]
	s_nop 0
	v_pk_fma_f32 v[16:17], v[2:3], v[70:71], v[16:17] op_sel_hi:[1,0,1] neg_lo:[0,0,1] neg_hi:[0,0,1]
	v_pk_mul_f32 v[2:3], v[200:201], v[82:83]
	s_nop 0
	v_pk_fma_f32 v[22:23], v[0:1], v[70:71], v[2:3] op_sel_hi:[1,0,1] neg_lo:[0,0,1] neg_hi:[0,0,1]
	s_nop 0
	v_pk_fma_f32 v[0:1], v[22:23], v[22:23], v[18:19]
	v_mul_f32_e32 v2, v23, v23
	v_pk_add_f32 v[0:1], v[0:1], v[2:3] op_sel_hi:[1,0]
	v_mul_f32_e32 v2, v17, v17
	v_pk_fma_f32 v[0:1], v[16:17], v[16:17], v[0:1]
	s_nop 0
	v_pk_add_f32 v[0:1], v[0:1], v[2:3] op_sel_hi:[1,0]
; __device__ __forceinline__ float half_swap_sum(float v) { auto rr = __builtin_amdgcn_permlane32_swap(__float_as_uint(v), __float_as_uint(v), false, false); return __uint_as_float(rr[0]) + __uint_as_float(rr[1]); }
; __device__ __forceinline__ void attn_item(LAS unsigned char* lds, const bf16_t* Q, const bf16_t* Kb, const bf16_t* VT, bf16_t* aout, const float* subg, float lam, float omli, float kbound, int head, int qb) {
;     ...
;             for (int i = 0; i < 16; ++i) { const float o = O[e][i] * inv - lam * X[(qt * 128 + 32 * e + (i & 3) + 8 * (i >> 2) + 4 * hh) * 32 + r]; O[e][i] = o; ss += o * o; }
;         ss = half_swap_sum(ss);
;         const float rn = __builtin_amdgcn_rsqf(ss * (1.f / 128.f) + EPS) * omli;
	v_pk_mul_f32 v[2:3], v[200:201], v[80:81]
	s_nop 0
	v_pk_fma_f32 v[6:7], v[6:7], v[70:71], v[2:3] op_sel_hi:[1,0,1] neg_lo:[0,0,1] neg_hi:[0,0,1]
	v_pk_mul_f32 v[2:3], v[200:201], v[78:79]
	s_nop 0
	v_pk_fma_f32 v[18:19], v[4:5], v[70:71], v[2:3] op_sel_hi:[1,0,1] neg_lo:[0,0,1] neg_hi:[0,0,1]
	v_pk_mul_f32 v[4:5], v[200:201], v[72:73]
	v_pk_fma_f32 v[0:1], v[18:19], v[18:19], v[0:1]
	v_mul_f32_e32 v2, v19, v19
	v_pk_add_f32 v[0:1], v[0:1], v[2:3] op_sel_hi:[1,0]
	v_mul_f32_e32 v2, v7, v7
	v_pk_fma_f32 v[0:1], v[6:7], v[6:7], v[0:1]
	v_pk_fma_f32 v[4:5], v[8:9], v[70:71], v[4:5] op_sel_hi:[1,0,1] neg_lo:[0,0,1] neg_hi:[0,0,1]
	v_pk_add_f32 v[2:3], v[0:1], v[2:3] op_sel_hi:[1,0]
	v_pk_mul_f32 v[0:1], v[200:201], v[76:77]
	v_pk_fma_f32 v[2:3], v[4:5], v[4:5], v[2:3]
	v_mul_f32_e32 v8, v5, v5
	v_pk_fma_f32 v[0:1], v[10:11], v[70:71], v[0:1] op_sel_hi:[1,0,1] neg_lo:[0,0,1] neg_hi:[0,0,1]
	v_pk_add_f32 v[2:3], v[2:3], v[8:9] op_sel_hi:[1,0]
	v_mul_f32_e32 v8, v1, v1
	v_pk_fma_f32 v[2:3], v[0:1], v[0:1], v[2:3]
	s_nop 0
	v_pk_add_f32 v[8:9], v[2:3], v[8:9] op_sel_hi:[1,0]
	v_pk_mul_f32 v[2:3], v[200:201], v[74:75]
	s_nop 0
	v_pk_fma_f32 v[2:3], v[12:13], v[70:71], v[2:3] op_sel_hi:[1,0,1] neg_lo:[0,0,1] neg_hi:[0,0,1]
	s_nop 0
	v_pk_fma_f32 v[8:9], v[2:3], v[2:3], v[8:9]
	v_mul_f32_e32 v10, v3, v3
	v_pk_add_f32 v[8:9], v[8:9], v[10:11] op_sel_hi:[1,0]
	v_mul_f32_e32 v10, v69, v69
	v_pk_fma_f32 v[8:9], v[68:69], v[68:69], v[8:9]
	s_nop 0
	v_pk_add_f32 v[8:9], v[8:9], v[10:11] op_sel_hi:[1,0]
	s_nop 0
	v_mov_b32_e32 v9, v8
	s_nop 1
	v_permlane32_swap_b32_e32 v8, v9
	v_add_f32_e32 v8, v8, v9
	v_fmamk_f32 v8, v8, 0x3c000000, v217
	v_rsq_f32_e32 v8, v8
	s_nop 0
	v_mul_f32_e32 v8, v224, v8
	v_pk_mul_f32 v[10:11], v[90:91], v[8:9] op_sel_hi:[1,0]
	v_pk_mul_f32 v[12:13], v[84:85], v[8:9] op_sel_hi:[1,0]
	s_waitcnt vmcnt(0)
; __device__ __forceinline__ unsigned pk2(float lo, float hi) { f32x2 v = {lo, hi}; bf16x2_t b = __builtin_convertvector(v, bf16x2_t); return __builtin_bit_cast(unsigned, b); }
; __device__ __forceinline__ void attn_item(LAS unsigned char* lds, const bf16_t* Q, const bf16_t* Kb, const bf16_t* VT, bf16_t* aout, const float* subg, float lam, float omli, float kbound, int head, int qb) {
;     ...
;         bf16_t* ap = aout + (size_t)q * 1024 + head * 128 + 4 * hh;
; #pragma unroll
;         for (int e = 0; e < 4; ++e)
; #pragma unroll
;             for (int g4 = 0; g4 < 4; ++g4) { const int e0 = 32 * e + 8 * g4; const f32x4 sg = *(const f32x4*)(subg + e0 + 4 * hh);
;                 u32x2 w; w.x = pk2(O[e][4 * g4 + 0] * rn * sg[0], O[e][4 * g4 + 1] * rn * sg[1]); w.y = pk2(O[e][4 * g4 + 2] * rn * sg[2], O[e][4 * g4 + 3] * rn * sg[3]);
;                 *(u32x2*)(ap + e0) = w; }
	v_pk_mul_f32 v[10:11], v[64:65], v[10:11]
	v_pk_mul_f32 v[12:13], v[66:67], v[12:13]
	v_cvt_pk_bf16_f32 v140, v10, v11
	v_cvt_pk_bf16_f32 v141, v12, v13
	v_pk_mul_f32 v[28:29], v[100:101], v[8:9] op_sel_hi:[1,0]
	v_pk_mul_f32 v[26:27], v[26:27], v[8:9] op_sel_hi:[1,0]
	v_pk_mul_f32 v[24:25], v[24:25], v[8:9] op_sel_hi:[1,0]
	v_pk_mul_f32 v[20:21], v[20:21], v[8:9] op_sel_hi:[1,0]
	v_pk_mul_f32 v[16:17], v[16:17], v[8:9] op_sel_hi:[1,0]
	v_pk_mul_f32 v[6:7], v[6:7], v[8:9] op_sel_hi:[1,0]
	v_pk_mul_f32 v[4:5], v[4:5], v[8:9] op_sel_hi:[1,0]
	v_pk_mul_f32 v[0:1], v[0:1], v[8:9] op_sel_hi:[1,0]
	v_pk_mul_f32 v[10:11], v[148:149], v[28:29]
	v_pk_mul_f32 v[28:29], v[92:93], v[8:9] op_sel_hi:[1,0]
	v_cvt_pk_bf16_f32 v142, v10, v11
	v_pk_mul_f32 v[12:13], v[150:151], v[28:29]
	v_pk_mul_f32 v[28:29], v[102:103], v[8:9] op_sel_hi:[1,0]
	v_cvt_pk_bf16_f32 v143, v12, v13
	v_lshrrev_b32_e32 v136, 1, v112
	v_mov_b32_e32 v137, 0
	v_lshl_add_u64 v[136:137], v[14:15], 0, v[136:137]
	s_nop 1
	v_permlane32_swap_b32_e32 v140, v142
	v_permlane32_swap_b32_e32 v141, v143
	global_store_dwordx4 v[136:137], v[140:143], off
	v_pk_mul_f32 v[10:11], v[152:153], v[28:29]
	v_pk_mul_f32 v[28:29], v[94:95], v[8:9] op_sel_hi:[1,0]
	v_cvt_pk_bf16_f32 v144, v10, v11
	v_pk_mul_f32 v[12:13], v[154:155], v[28:29]
	v_pk_mul_f32 v[28:29], v[62:63], v[8:9] op_sel_hi:[1,0]
	v_cvt_pk_bf16_f32 v145, v12, v13
	v_pk_mul_f32 v[10:11], v[156:157], v[28:29]
	v_pk_mul_f32 v[28:29], v[58:59], v[8:9] op_sel_hi:[1,0]
	v_cvt_pk_bf16_f32 v146, v10, v11
	v_pk_mul_f32 v[12:13], v[158:159], v[28:29]
	v_pk_mul_f32 v[28:29], v[60:61], v[8:9] op_sel_hi:[1,0]
	v_cvt_pk_bf16_f32 v147, v12, v13
	s_nop 1
	v_permlane32_swap_b32_e32 v144, v146
	v_permlane32_swap_b32_e32 v145, v147
	global_store_dwordx4 v[136:137], v[144:147], off offset:32
	v_pk_mul_f32 v[10:11], v[28:29], v[160:161]
	v_pk_mul_f32 v[28:29], v[54:55], v[8:9] op_sel_hi:[1,0]
	v_cvt_pk_bf16_f32 v140, v10, v11
	v_pk_mul_f32 v[12:13], v[28:29], v[162:163]
	v_pk_mul_f32 v[28:29], v[56:57], v[8:9] op_sel_hi:[1,0]
	v_cvt_pk_bf16_f32 v141, v12, v13
	v_pk_mul_f32 v[10:11], v[28:29], v[164:165]
	v_pk_mul_f32 v[28:29], v[50:51], v[8:9] op_sel_hi:[1,0]
	v_cvt_pk_bf16_f32 v142, v10, v11
	v_pk_mul_f32 v[12:13], v[28:29], v[166:167]
	v_pk_mul_f32 v[28:29], v[52:53], v[8:9] op_sel_hi:[1,0]
	v_cvt_pk_bf16_f32 v143, v12, v13
	s_nop 1
	v_permlane32_swap_b32_e32 v140, v142
	v_permlane32_swap_b32_e32 v141, v143
	global_store_dwordx4 v[136:137], v[140:143], off offset:64
	v_pk_mul_f32 v[10:11], v[28:29], v[168:169]
	v_pk_mul_f32 v[28:29], v[48:49], v[8:9] op_sel_hi:[1,0]
	v_cvt_pk_bf16_f32 v144, v10, v11
	v_pk_mul_f32 v[12:13], v[28:29], v[170:171]
	v_pk_mul_f32 v[28:29], v[44:45], v[8:9] op_sel_hi:[1,0]
	v_cvt_pk_bf16_f32 v145, v12, v13
	v_pk_mul_f32 v[10:11], v[28:29], v[176:177]
	v_pk_mul_f32 v[28:29], v[40:41], v[8:9] op_sel_hi:[1,0]
	v_cvt_pk_bf16_f32 v146, v10, v11
	v_pk_mul_f32 v[12:13], v[28:29], v[178:179]
	v_pk_mul_f32 v[28:29], v[42:43], v[8:9] op_sel_hi:[1,0]
	v_cvt_pk_bf16_f32 v147, v12, v13
	s_nop 1
	v_permlane32_swap_b32_e32 v144, v146
	v_permlane32_swap_b32_e32 v145, v147
	global_store_dwordx4 v[136:137], v[144:147], off offset:96
	v_pk_mul_f32 v[10:11], v[28:29], v[184:185]
	v_pk_mul_f32 v[28:29], v[36:37], v[8:9] op_sel_hi:[1,0]
	v_cvt_pk_bf16_f32 v140, v10, v11
	v_pk_mul_f32 v[12:13], v[28:29], v[186:187]
	v_pk_mul_f32 v[28:29], v[38:39], v[8:9] op_sel_hi:[1,0]
	v_cvt_pk_bf16_f32 v141, v12, v13
	v_pk_mul_f32 v[10:11], v[28:29], v[204:205]
	v_pk_mul_f32 v[28:29], v[32:33], v[8:9] op_sel_hi:[1,0]
	v_cvt_pk_bf16_f32 v142, v10, v11
	v_pk_mul_f32 v[12:13], v[28:29], v[206:207]
	v_pk_mul_f32 v[28:29], v[34:35], v[8:9] op_sel_hi:[1,0]
	v_cvt_pk_bf16_f32 v143, v12, v13
	s_nop 1
	v_permlane32_swap_b32_e32 v140, v142
	v_permlane32_swap_b32_e32 v141, v143
	global_store_dwordx4 v[136:137], v[140:143], off offset:128
	v_pk_mul_f32 v[10:11], v[28:29], v[208:209]
	v_pk_mul_f32 v[12:13], v[26:27], v[210:211]
	v_cvt_pk_bf16_f32 v144, v10, v11
	v_cvt_pk_bf16_f32 v145, v12, v13
	v_pk_mul_f32 v[10:11], v[24:25], v[232:233]
	v_pk_mul_f32 v[12:13], v[20:21], v[234:235]
	v_cvt_pk_bf16_f32 v146, v10, v11
	v_cvt_pk_bf16_f32 v147, v12, v13
	s_nop 1
	v_permlane32_swap_b32_e32 v144, v146
	v_permlane32_swap_b32_e32 v145, v147
	global_store_dwordx4 v[136:137], v[144:147], off offset:160
	v_pk_mul_f32 v[20:21], v[22:23], v[8:9] op_sel_hi:[1,0]
	v_pk_mul_f32 v[12:13], v[16:17], v[238:239]
	v_pk_mul_f32 v[10:11], v[20:21], v[236:237]
	v_pk_mul_f32 v[16:17], v[18:19], v[8:9] op_sel_hi:[1,0]
	v_cvt_pk_bf16_f32 v140, v10, v11
	v_cvt_pk_bf16_f32 v141, v12, v13
	v_pk_mul_f32 v[10:11], v[16:17], v[240:241]
	v_pk_mul_f32 v[6:7], v[6:7], v[242:243]
	v_cvt_pk_bf16_f32 v142, v10, v11
	v_cvt_pk_bf16_f32 v143, v6, v7
	s_nop 1
	v_permlane32_swap_b32_e32 v140, v142
	v_permlane32_swap_b32_e32 v141, v143
	global_store_dwordx4 v[136:137], v[140:143], off offset:192
	v_pk_mul_f32 v[4:5], v[4:5], v[244:245]
	v_pk_mul_f32 v[0:1], v[0:1], v[246:247]
	v_cvt_pk_bf16_f32 v144, v4, v5
	v_cvt_pk_bf16_f32 v145, v0, v1
	v_pk_mul_f32 v[0:1], v[2:3], v[8:9] op_sel_hi:[1,0]
	v_pk_mul_f32 v[2:3], v[68:69], v[8:9] op_sel_hi:[1,0]
	v_pk_mul_f32 v[0:1], v[0:1], v[248:249]
	v_pk_mul_f32 v[2:3], v[2:3], v[250:251]
	v_cvt_pk_bf16_f32 v146, v0, v1
	v_cvt_pk_bf16_f32 v147, v2, v3
	s_nop 1
	v_permlane32_swap_b32_e32 v144, v146
	v_permlane32_swap_b32_e32 v145, v147
	global_store_dwordx4 v[136:137], v[144:147], off offset:224
	s_branch .LBB0_291
